# v32: v22 + attention tile-(i+2) K/V loads addressed as SGPR base + 32-bit VGPR offsets (v_mad_u32_u24 + 4 v_add_u32 instead of v_mad_i64_i32 + 5 v_lshl_add_u64 per tile)
# speedup vs baseline: 1.0080x; 1.0080x over previous
; template <int PM> DI void attn_phase(const Params& p, int l, char* smem, int* s_item, int wv, int cidx) {
;   int lane_; asm volatile("v_mbcnt_lo_u32_b32 %0, -1, 0\n\tv_mbcnt_hi_u32_b32 %0, -1, %0" : "=v"(lane_)); asm volatile("" : "+s"(wv));
;   const int tid_ = wv * 64 + lane_;
;   const int tid = tid_, lane = lane_, w = wv, h = lane >> 5, l31 = lane & 31;
;   const int n_items = 512 + (l < 3 ? 64 : 0);
;   char* Kb0 = smem;
;   char* Vb0 = smem + 34816;
;   float* rpb_s = (float*)(smem + 75776);
;   float* sg_s = (float*)(smem + 77696);
;   char* gate_s = smem + 78336;
;   if (tid < 128) sg_s[tid] = p.subln_g[l * 128 + tid];
;   const float li_ = (l == 0) ? 0.2f : (l == 1) ? 0.35550906759096926f : (l == 2) ? 0.47071301834358416f : 0.5560582041556405f;
;   const float lambda_init = __uint_as_float(__builtin_amdgcn_readfirstlane(__float_as_uint(li_)));
;   float lam;
;   {
;     float d1 = p.lq1[l * 64 + lane] * p.lk1[l * 64 + lane];
;     float d2 = p.lq2[l * 64 + lane] * p.lk2[l * 64 + lane];
;     d1 = wave_sum(d1); d2 = wave_sum(d2);
;     lam = expf(d1) - expf(d2) + lambda_init;
;     lam = __uint_as_float(__builtin_amdgcn_readfirstlane(__float_as_uint(lam)));
;   }
;   const int trow = tid >> 4, tch = tid & 15;
;     ...
;         const u16* base = p.P + (size_t)(Rb + trow) * INW + tch * 8;
; #pragma unroll
;         for (int j = 0; j < 2; ++j) {
;           kst[j] = *(const u32x4*)(base + (size_t)j * 32 * INW + koff);
;           vst[j] = *(const u32x4*)(base + (size_t)j * 32 * INW + voff);
;         }
; #pragma unroll
;         for (int j = 0; j < 2; ++j) {
;           *(u32x4*)(Kb0 + (trow + 32 * j) * 272 + tch * 16) = kst[j];
;           *(u32x4*)(Vb0 + (trow + 32 * j) * 320 + tch * 16) = vst[j];
;         }
;         const int R1 = (1 < nplain) ? Rb + 64 : Rb + 256 + local_t0 + 64 * (1 - nplain);
;         const u16* b1 = p.P + (size_t)(R1 + trow) * INW + tch * 8;
;         if (ntl > 1) {
; #pragma unroll
;           for (int j = 0; j < 2; ++j) {
;             kst[j] = *(const u32x4*)(b1 + (size_t)j * 32 * INW + koff);
;             vst[j] = *(const u32x4*)(b1 + (size_t)j * 32 * INW + voff);
;           }
;         }
;       }
;       __syncthreads();
;       const bool shift = ATT_SKEW && (w >= 4);
;       bool pend = false;
;       int vcur = 0;
;       bf16x8 pf[2][2];
; #pragma unroll
;       for (int kb = 0; kb < 2; ++kb)
; #pragma unroll
.LBB0_375:
	s_or_b64 exec, exec, s[0:1]
	s_and_b64 s[0:1], s[82:83], exec
	s_movk_i32 s0, 0x240
	s_cselect_b32 s3, s0, 0x200
	s_and_b32 s0, s81, -4
	v_writelane_b32 v254, s0, 54
	s_movk_i32 s0, 0x1d1
	v_and_b32_e32 v2, 15, v0
	v_ashrrev_i32_e32 v3, 5, v0
	v_cmp_gt_i32_e64 s[0:1], s0, v238
	v_lshlrev_b32_e32 v32, 3, v2
	v_lshlrev_b32_e32 v196, 4, v2
	v_writelane_b32 v254, s0, 55
	v_lshlrev_b32_e32 v198, 2, v3
	v_lshrrev_b32_e32 v2, 2, v0
	v_and_b32_e32 v240, 31, v0
	v_writelane_b32 v254, s1, 56
	v_and_or_b32 v2, v2, 3, v198
	s_movk_i32 s0, 0x140
	v_and_b32_e32 v4, 16, v0
	v_lshlrev_b32_e32 v0, 2, v0
	s_lshl_b32 s6, s5, 5
	v_mul_lo_u32 v2, v2, s0
	v_and_or_b32 v0, v0, 12, v4
	v_ashrrev_i32_e32 v239, 4, v238
	v_or_b32_e32 v241, s6, v240
	v_lshlrev_b32_e32 v200, 3, v3
	v_lshl_or_b32 v242, v0, 1, v2
	v_lshlrev_b32_e32 v0, 4, v3
	s_movk_i32 s1, 0x110
	v_sub_f32_e64 v244, 1.0, s8
	s_movk_i32 s2, 0x108
	v_readlane_b32 s8, v253, 21
	v_or_b32_e32 v33, 0x13200, v196
	v_add_u32_e32 v34, 0x13200, v200
	v_mad_u32_u24 v243, v240, s1, v0
	v_mul_lo_u32 v35, v241, s2
	v_add_u32_e32 v245, 0x12f80, v0
	v_mul_lo_u32 v36, v239, s2
	v_mov_b32_e32 v197, v1
	v_readlane_b32 s22, v253, 35
	v_readlane_b32 s23, v253, 36
	v_sub_u32_e32 v0, v198, v240
	v_mov_b32_e32 v16, v1
	v_mov_b32_e32 v17, v1
	v_mov_b32_e32 v18, v1
	v_mov_b32_e32 v19, v1
	v_mov_b32_e32 v20, v1
	v_mov_b32_e32 v21, v1
	v_mov_b32_e32 v22, v1
	v_mov_b32_e32 v23, v1
	v_mov_b32_e32 v24, v1
	v_mov_b32_e32 v25, v1
	v_mov_b32_e32 v26, v1
	v_mov_b32_e32 v27, v1
	v_mov_b32_e32 v28, v1
	v_mov_b32_e32 v29, v1
	v_mov_b32_e32 v30, v1
	v_mov_b32_e32 v31, v1
	v_readlane_b32 s16, v253, 29
	v_readlane_b32 s18, v253, 31
	v_readlane_b32 s19, v253, 32
	v_readlane_b32 s20, v253, 33
	v_lshl_add_u64 v[202:203], s[22:23], 0, v[196:197]
	s_mov_b64 s[100:101], s[22:23]
	v_writelane_b32 v254, s6, 57
	v_subrev_u32_e32 v197, s6, v0
	v_mov_b32_e32 v0, v1
	v_mov_b32_e32 v2, v1
	v_mov_b32_e32 v3, v1
	v_mov_b32_e32 v4, v1
	v_mov_b32_e32 v5, v1
	v_mov_b32_e32 v6, v1
	v_mov_b32_e32 v7, v1
	v_mov_b32_e32 v8, v1
	v_mov_b32_e32 v9, v1
	v_mov_b32_e32 v10, v1
	v_mov_b32_e32 v11, v1
	v_mov_b32_e32 v12, v1
	v_mov_b32_e32 v13, v1
	v_mov_b32_e32 v14, v1
	v_mov_b32_e32 v15, v1
	v_lshlrev_b32_e32 v204, 1, v32
	v_add_u32_e32 v251, v33, v36
	v_add_u32_e32 v252, v34, v35
	v_mov_b64_e32 v[46:47], v[30:31]
	v_ashrrev_i32_e32 v199, 31, v198
	v_ashrrev_i32_e32 v201, 31, v200
	v_mul_lo_u32 v246, v239, s1
	v_mul_lo_u32 v247, v239, s0
	v_or_b32_e32 v248, 1, v198
	v_or_b32_e32 v249, 2, v198
	v_or_b32_e32 v250, 3, v198
	s_mov_b32 s5, s4
	v_mov_b64_e32 v[44:45], v[28:29]
	v_mov_b64_e32 v[42:43], v[26:27]
	v_mov_b64_e32 v[40:41], v[24:25]
	v_mov_b64_e32 v[38:39], v[22:23]
	v_mov_b64_e32 v[36:37], v[20:21]
	v_mov_b64_e32 v[34:35], v[18:19]
	v_mov_b64_e32 v[32:33], v[16:17]
	v_mov_b64_e32 v[30:31], v[14:15]
	v_mov_b64_e32 v[28:29], v[12:13]
	v_mov_b64_e32 v[26:27], v[10:11]
	v_mov_b64_e32 v[24:25], v[8:9]
	v_mov_b64_e32 v[22:23], v[6:7]
	v_mov_b64_e32 v[20:21], v[4:5]
	v_mov_b64_e32 v[18:19], v[2:3]
	v_mov_b64_e32 v[16:17], v[0:1]
	s_mov_b32 s19, s35
	s_movk_i32 s20, 0x6000
	s_mov_b32 s18, 0x1e000
	s_movk_i32 s16, 0x7f
	v_writelane_b32 v254, s3, 58
	v_readlane_b32 s9, v253, 22
	v_readlane_b32 s10, v253, 23
	v_readlane_b32 s11, v253, 24
	v_readlane_b32 s12, v253, 25
	v_readlane_b32 s13, v253, 26
	v_readlane_b32 s14, v253, 27
	v_readlane_b32 s15, v253, 28
	v_readlane_b32 s17, v253, 30
	v_readlane_b32 s21, v253, 34
	s_branch .LBB0_378

; template <int PM> DI void attn_phase(const Params& p, int l, char* smem, int* s_item, int wv, int cidx) {
;     ...
;         if (PM != 2 && i + 2 < ntl) {
;           const int inx = i + 2;
;           const int Rn = (inx < nplain) ? Rb + 64 * inx : Rb + 256 + local_t0 + 64 * (inx - nplain);
;           const u16* nbase = p.P + (size_t)(Rn + trow) * INW + tch * 8;
; #pragma unroll
;           for (int j = 0; j < 2; ++j) {
;             kst[j] = *(const u32x4*)(nbase + (size_t)j * 32 * INW + koff);
;             vst[j] = *(const u32x4*)(nbase + (size_t)j * 32 * INW + voff);
;           }
;         }
.LBB0_429:
	v_add_u32_e32 v0, s74, v239
	v_mad_u32_u24 v2, v0, s85, v196
	v_add_u32_e32 v4, s96, v2
	v_add_u32_e32 v5, s76, v2
	v_add_u32_e32 v6, 0x70000, v4
	v_add_u32_e32 v7, 0x70000, v5
	global_load_dwordx4 v[180:183], v4, s[100:101]
	global_load_dwordx4 v[184:187], v5, s[100:101]
	global_load_dwordx4 v[188:191], v6, s[100:101]
	global_load_dwordx4 v[192:195], v7, s[100:101]

; __global__ void __launch_bounds__(512, 1) mega_kernel(Params p) {
;   __shared__ __attribute__((aligned(16))) char smem[SMEM_BYTES + 16];
	.amdhsa_kernel _Z11mega_kernel6Params
		.amdhsa_group_segment_fixed_size 147472
		.amdhsa_private_segment_fixed_size 0
		.amdhsa_kernarg_size 544
		.amdhsa_user_sgpr_count 2
		.amdhsa_user_sgpr_dispatch_ptr 0
		.amdhsa_user_sgpr_queue_ptr 0
		.amdhsa_user_sgpr_kernarg_segment_ptr 1
		.amdhsa_user_sgpr_dispatch_id 0
		.amdhsa_user_sgpr_kernarg_preload_length 0
		.amdhsa_user_sgpr_kernarg_preload_offset 0
		.amdhsa_user_sgpr_private_segment_size 0
		.amdhsa_uses_dynamic_stack 0
		.amdhsa_enable_private_segment 0
		.amdhsa_system_sgpr_workgroup_id_x 1
		.amdhsa_system_sgpr_workgroup_id_y 0
		.amdhsa_system_sgpr_workgroup_id_z 0
		.amdhsa_system_sgpr_workgroup_info 0
		.amdhsa_system_vgpr_workitem_id 2
		.amdhsa_next_free_vgpr 256
		.amdhsa_next_free_sgpr 102
		.amdhsa_accum_offset 256
		.amdhsa_reserve_vcc 1
		.amdhsa_float_round_mode_32 0
		.amdhsa_float_round_mode_16_64 0
		.amdhsa_float_denorm_mode_32 3
		.amdhsa_float_denorm_mode_16_64 3
		.amdhsa_dx10_clamp 1
		.amdhsa_ieee_mode 1
		.amdhsa_fp16_overflow 0
		.amdhsa_tg_split 0
		.amdhsa_exception_fp_ieee_invalid_op 0
		.amdhsa_exception_fp_denorm_src 0
		.amdhsa_exception_fp_ieee_div_zero 0
		.amdhsa_exception_fp_ieee_overflow 0
		.amdhsa_exception_fp_ieee_underflow 0
		.amdhsa_exception_fp_ieee_inexact 0
		.amdhsa_exception_int_div_zero 0
	.end_amdhsa_kernel

amdhsa.kernels:
  - .agpr_count:     0
    .args:
      - .offset:         0
        .size:           288
        .value_kind:     by_value
      - .offset:         288
        .size:           4
        .value_kind:     hidden_block_count_x
      - .offset:         292
        .size:           4
        .value_kind:     hidden_block_count_y
      - .offset:         296
        .size:           4
        .value_kind:     hidden_block_count_z
      - .offset:         300
        .size:           2
        .value_kind:     hidden_group_size_x
      - .offset:         302
        .size:           2
        .value_kind:     hidden_group_size_y
      - .offset:         304
        .size:           2
        .value_kind:     hidden_group_size_z
      - .offset:         306
        .size:           2
        .value_kind:     hidden_remainder_x
      - .offset:         308
        .size:           2
        .value_kind:     hidden_remainder_y
      - .offset:         310
        .size:           2
        .value_kind:     hidden_remainder_z
      - .offset:         328
        .size:           8
        .value_kind:     hidden_global_offset_x
      - .offset:         336
        .size:           8
        .value_kind:     hidden_global_offset_y
      - .offset:         344
        .size:           8
        .value_kind:     hidden_global_offset_z
      - .offset:         352
        .size:           2
        .value_kind:     hidden_grid_dims
      - .offset:         376
        .size:           8
        .value_kind:     hidden_multigrid_sync_arg
    .group_segment_fixed_size: 147472
    .kernarg_segment_align: 8
    .kernarg_segment_size: 544
    .language:       OpenCL C
    .language_version:
      - 2
      - 0
    .max_flat_workgroup_size: 512
    .name:           _Z11mega_kernel6Params
    .private_segment_fixed_size: 0
    .sgpr_count:     108
    .sgpr_spill_count: 142
    .symbol:         _Z11mega_kernel6Params.kd
    .uniform_work_group_size: 1
    .uses_dynamic_stack: false
    .vgpr_count:     256
    .vgpr_spill_count: 0
    .wavefront_size: 64
